# MLA loop-edge: bookkeeping and next-tile tests ahead of the softmax-closing barrier, ballot trimmed, first P.V reads issued in the QK^T tail
# baseline (speedup 1.0000x reference)
.LBB0_526:
	s_add_i32 s8, s97, s96
	s_add_i32 s7, s8, -2
	s_cmp_lt_i32 s7, 0
	s_cselect_b64 s[4:5], -1, 0
	s_cmp_le_i32 s95, s68
	s_cselect_b64 s[12:13], -1, 0
	s_or_b64 s[12:13], s[4:5], s[12:13]
	s_andn2_b64 s[4:5], exec, s[12:13]
	s_add_i32 s14, s8, -3
	s_cmp_gt_i32 s14, -1
	s_cselect_b64 s[14:15], -1, 0
	s_sub_i32 s20, s95, 64
	s_cmp_gt_i32 s20, s68
	s_cselect_b64 s[28:29], -1, 0
	s_and_b64 s[14:15], s[14:15], s[28:29]
	s_cmp_eq_u32 s96, 2
	s_cselect_b64 s[28:29], -1, 0
	s_or_b64 s[14:15], s[14:15], s[28:29]
	v_lshl_add_u32 v254, s6, 14, v202
	s_andn2_b64 vcc, exec, s[12:13]
	s_mov_b32 s72, s10
	s_cbranch_vccnz .LBB0_528
	s_mul_i32 s9, s72, 0x6000
	v_add_u32_e32 v0, s9, v193
	s_branch .Lmla_qk_body
.Lmla_fast_edge:
	s_add_i32 s7, s2, 1
	s_add_i32 s2, s86, 1
	s_cmp_lg_u32 s86, 2
	s_cselect_b32 s2, s2, 0
	s_add_i32 s95, s95, 64
	s_add_i32 s96, s96, 1
	s_mov_b64 s[4:5], 0x20000
	v_lshl_add_u64 v[178:179], v[178:179], 0, s[4:5]
	v_lshl_add_u64 v[180:181], v[180:181], 0, s[88:89]
	v_lshl_add_u64 v[182:183], v[182:183], 0, s[88:89]
	v_subrev_u32_e32 v177, 64, v177
	s_mov_b32 s10, s86
	s_mov_b32 s6, s72
	s_mov_b32 s86, s2
	s_mov_b32 s2, s7
	s_add_i32 s8, s97, s96
	s_add_i32 s7, s8, -2
	s_cmp_lt_i32 s7, 0
	s_cselect_b64 s[4:5], -1, 0
	s_cmp_le_i32 s95, s68
	s_cselect_b64 s[12:13], -1, 0
	s_or_b64 s[12:13], s[4:5], s[12:13]
	s_andn2_b64 s[4:5], exec, s[12:13]
	s_add_i32 s14, s8, -3
	s_cmp_gt_i32 s14, -1
	s_cselect_b64 s[14:15], -1, 0
	s_sub_i32 s20, s95, 64
	s_cmp_gt_i32 s20, s68
	s_cselect_b64 s[28:29], -1, 0
	s_and_b64 s[14:15], s[14:15], s[28:29]
	v_lshl_add_u32 v254, s6, 14, v202
	s_mov_b32 s72, s10
	s_mul_i32 s9, s72, 0x6000
	v_add_u32_e32 v0, s9, v193
	s_andn2_b64 vcc, exec, s[12:13]
	s_waitcnt vmcnt(10) lgkmcnt(0)
	s_barrier
	s_cbranch_vccnz .LBB0_528
.Lmla_qk_body:
	ds_read_b128 v[2:5], v0 offset:0
	ds_read_b128 v[6:9], v0 offset:0x2000
	v_add_u32_e32 v14, s9, v195
	ds_read_b128 v[10:13], v14 offset:0
	ds_read_b128 v[210:213], v14 offset:0x2000
	v_add_u32_e32 v15, s9, v197
	ds_read_b128 v[214:217], v15 offset:0
	s_waitcnt lgkmcnt(4)
	v_add_u32_e32 v209, s9, v199
	v_mfma_f32_32x32x16_bf16 v[80:95], v[2:5], v[112:115], 0
	ds_read_b128 v[2:5], v15 offset:0x2000
	s_waitcnt lgkmcnt(4)
	s_nop 0
	v_mfma_f32_32x32x16_bf16 v[96:111], v[6:9], v[112:115], 0
	ds_read_b128 v[6:9], v209 offset:0
	s_waitcnt lgkmcnt(4)
	s_nop 0
	v_mfma_f32_32x32x16_bf16 v[80:95], v[10:13], v[116:119], v[80:95]
	ds_read_b128 v[10:13], v209 offset:0x2000
	s_waitcnt lgkmcnt(4)
	s_nop 0
	v_mfma_f32_32x32x16_bf16 v[96:111], v[210:213], v[116:119], v[96:111]
	ds_read_b128 v[210:213], v0 offset:0x80
	s_waitcnt lgkmcnt(4)
	s_nop 0
	v_mfma_f32_32x32x16_bf16 v[80:95], v[214:217], v[120:123], v[80:95]
	ds_read_b128 v[214:217], v0 offset:0x2080
	s_waitcnt lgkmcnt(4)
	v_add_u32_e32 v0, s9, v194
	v_mfma_f32_32x32x16_bf16 v[96:111], v[2:5], v[120:123], v[96:111]
	ds_read_b128 v[2:5], v14 offset:0x80
	s_waitcnt lgkmcnt(4)
	s_nop 0
	v_mfma_f32_32x32x16_bf16 v[80:95], v[6:9], v[124:127], v[80:95]
	ds_read_b128 v[6:9], v14 offset:0x2080
	s_waitcnt lgkmcnt(4)
	s_nop 0
	v_mfma_f32_32x32x16_bf16 v[96:111], v[10:13], v[124:127], v[96:111]
	ds_read_b128 v[10:13], v15 offset:0x80
	s_waitcnt lgkmcnt(4)
	s_nop 0
	v_mfma_f32_32x32x16_bf16 v[80:95], v[210:213], v[128:131], v[80:95]
	ds_read_b128 v[210:213], v15 offset:0x2080
	s_waitcnt lgkmcnt(4)
	s_nop 0
	v_mfma_f32_32x32x16_bf16 v[96:111], v[214:217], v[128:131], v[96:111]
	ds_read_b128 v[214:217], v209 offset:0x80
	s_waitcnt lgkmcnt(4)
	s_nop 0
	v_mfma_f32_32x32x16_bf16 v[80:95], v[2:5], v[132:135], v[80:95]
	ds_read_b128 v[2:5], v209 offset:0x2080
	s_waitcnt lgkmcnt(4)
	s_nop 0
	v_mfma_f32_32x32x16_bf16 v[96:111], v[6:9], v[132:135], v[96:111]
	ds_read_b128 v[6:9], v0 offset:0
	ds_read_b128 v[218:221], v169 offset:0
	s_waitcnt lgkmcnt(5)
	s_nop 0
	v_mfma_f32_32x32x16_bf16 v[80:95], v[10:13], v[136:139], v[80:95]
	ds_read_b128 v[10:13], v0 offset:0x1000
	s_waitcnt lgkmcnt(5)
	v_add_u32_e32 v0, s9, v196
	v_mfma_f32_32x32x16_bf16 v[96:111], v[210:213], v[136:139], v[96:111]
	ds_read_b128 v[210:213], v0 offset:0
	ds_read_b128 v[222:225], v169 offset:0x400
	s_waitcnt lgkmcnt(6)
	s_nop 0
	v_mfma_f32_32x32x16_bf16 v[80:95], v[214:217], v[140:143], v[80:95]
	ds_read_b128 v[214:217], v0 offset:0x1000
	s_waitcnt lgkmcnt(6)
	v_add_u32_e32 v0, s9, v198
	v_mfma_f32_32x32x16_bf16 v[96:111], v[2:5], v[140:143], v[96:111]
	ds_read_b128 v[2:5], v0 offset:0
	ds_read_b128 v[226:229], v169 offset:0x800
	s_waitcnt lgkmcnt(6)
	s_nop 0
	v_mfma_f32_32x32x16_bf16 v[80:95], v[6:9], v[218:221], v[80:95]
	ds_read_b128 v[6:9], v0 offset:0x1000
	s_waitcnt lgkmcnt(6)
	v_add_u32_e32 v0, s9, v200
	v_mfma_f32_32x32x16_bf16 v[96:111], v[10:13], v[218:221], v[96:111]
	ds_read_b128 v[10:13], v0 offset:0
	ds_read_b128 v[218:221], v169 offset:0xc00
	s_waitcnt lgkmcnt(6)
	s_nop 0
	v_mfma_f32_32x32x16_bf16 v[80:95], v[210:213], v[222:225], v[80:95]
	ds_read_b128 v[210:213], v0 offset:0x1000
	ds_read_b64_tr_b16 v[230:231], v254 offset:0
	ds_read_b64_tr_b16 v[232:233], v254 offset:0x800
	s_waitcnt lgkmcnt(8)
	v_mfma_f32_32x32x16_bf16 v[96:111], v[214:217], v[222:225], v[96:111]
	ds_read_b64_tr_b16 v[234:235], v254 offset:0x1000
	ds_read_b64_tr_b16 v[236:237], v254 offset:0x1800
	s_waitcnt lgkmcnt(8)
	v_mfma_f32_32x32x16_bf16 v[80:95], v[2:5], v[226:229], v[80:95]
	ds_read_b64_tr_b16 v[238:239], v254 offset:0x2000
	ds_read_b64_tr_b16 v[240:241], v254 offset:0x2800
	s_waitcnt lgkmcnt(9)
	v_mfma_f32_32x32x16_bf16 v[96:111], v[6:9], v[226:229], v[96:111]
	ds_read_b64_tr_b16 v[242:243], v254 offset:0x3000
	ds_read_b64_tr_b16 v[244:245], v254 offset:0x3800
	s_waitcnt lgkmcnt(9)
	v_mfma_f32_32x32x16_bf16 v[80:95], v[10:13], v[218:221], v[80:95]
	s_waitcnt lgkmcnt(8)
	v_mfma_f32_32x32x16_bf16 v[96:111], v[210:213], v[218:221], v[96:111]
	s_and_b64 vcc, exec, s[14:15]
	s_cbranch_vccnz .LBB0_531
.Lmla_pv_go:
	s_waitcnt lgkmcnt(6)
	v_mfma_f32_32x32x16_bf16 v[64:79], v[230:233], v[156:159], v[64:79]
	ds_read_b64_tr_b16 v[2:3], v254 offset:0x200
	ds_read_b64_tr_b16 v[4:5], v254 offset:0xa00
	s_waitcnt lgkmcnt(6)
	v_mfma_f32_32x32x16_bf16 v[64:79], v[234:237], v[152:155], v[64:79]
	ds_read_b64_tr_b16 v[6:7], v254 offset:0x1200
	ds_read_b64_tr_b16 v[8:9], v254 offset:0x1a00
	s_waitcnt lgkmcnt(6)
	v_mfma_f32_32x32x16_bf16 v[64:79], v[238:241], v[148:151], v[64:79]
	ds_read_b64_tr_b16 v[10:11], v254 offset:0x2200
	ds_read_b64_tr_b16 v[12:13], v254 offset:0x2a00
	s_waitcnt lgkmcnt(6)
	v_mfma_f32_32x32x16_bf16 v[64:79], v[242:245], v[144:147], v[64:79]
	ds_read_b64_tr_b16 v[210:211], v254 offset:0x3200
	ds_read_b64_tr_b16 v[212:213], v254 offset:0x3a00
	s_waitcnt lgkmcnt(6)
	v_mfma_f32_32x32x16_bf16 v[48:63], v[2:5], v[156:159], v[48:63]
	ds_read_b64_tr_b16 v[2:3], v254 offset:0x400
	ds_read_b64_tr_b16 v[4:5], v254 offset:0xc00
	s_waitcnt lgkmcnt(6)
	v_mfma_f32_32x32x16_bf16 v[48:63], v[6:9], v[152:155], v[48:63]
	ds_read_b64_tr_b16 v[6:7], v254 offset:0x1400
	ds_read_b64_tr_b16 v[8:9], v254 offset:0x1c00
	s_waitcnt lgkmcnt(6)
	v_mfma_f32_32x32x16_bf16 v[48:63], v[10:13], v[148:151], v[48:63]
	ds_read_b64_tr_b16 v[10:11], v254 offset:0x2400
	ds_read_b64_tr_b16 v[12:13], v254 offset:0x2c00
	s_waitcnt lgkmcnt(6)
	v_mfma_f32_32x32x16_bf16 v[48:63], v[210:213], v[144:147], v[48:63]
	ds_read_b64_tr_b16 v[210:211], v254 offset:0x3400
	ds_read_b64_tr_b16 v[212:213], v254 offset:0x3c00
	s_waitcnt lgkmcnt(6)
	v_mfma_f32_32x32x16_bf16 v[32:47], v[2:5], v[156:159], v[32:47]
	ds_read_b64_tr_b16 v[2:3], v254 offset:0x600
	ds_read_b64_tr_b16 v[4:5], v254 offset:0xe00
	s_waitcnt lgkmcnt(6)
	v_mfma_f32_32x32x16_bf16 v[32:47], v[6:9], v[152:155], v[32:47]
	ds_read_b64_tr_b16 v[6:7], v254 offset:0x1600
	ds_read_b64_tr_b16 v[8:9], v254 offset:0x1e00
	s_waitcnt lgkmcnt(6)
	v_mfma_f32_32x32x16_bf16 v[32:47], v[10:13], v[148:151], v[32:47]
	ds_read_b64_tr_b16 v[10:11], v254 offset:0x2600
	ds_read_b64_tr_b16 v[12:13], v254 offset:0x2e00
	s_waitcnt lgkmcnt(6)
	v_mfma_f32_32x32x16_bf16 v[32:47], v[210:213], v[144:147], v[32:47]
	ds_read_b64_tr_b16 v[210:211], v254 offset:0x3600
	ds_read_b64_tr_b16 v[212:213], v254 offset:0x3e00
	s_waitcnt lgkmcnt(6)
	v_mfma_f32_32x32x16_bf16 v[16:31], v[2:5], v[156:159], v[16:31]
	s_waitcnt lgkmcnt(4)
	v_mfma_f32_32x32x16_bf16 v[16:31], v[6:9], v[152:155], v[16:31]
	s_waitcnt lgkmcnt(2)
	v_mfma_f32_32x32x16_bf16 v[16:31], v[10:13], v[148:151], v[16:31]
	s_waitcnt lgkmcnt(0)
	v_mfma_f32_32x32x16_bf16 v[16:31], v[210:213], v[144:147], v[16:31]

.LBB0_528:
	s_and_b64 vcc, exec, s[14:15]
	s_cbranch_vccnz .LBB0_531
	ds_read_b64_tr_b16 v[230:231], v254 offset:0
	ds_read_b64_tr_b16 v[232:233], v254 offset:0x800
	ds_read_b64_tr_b16 v[234:235], v254 offset:0x1000
	ds_read_b64_tr_b16 v[236:237], v254 offset:0x1800
	ds_read_b64_tr_b16 v[238:239], v254 offset:0x2000
	ds_read_b64_tr_b16 v[240:241], v254 offset:0x2800
	ds_read_b64_tr_b16 v[242:243], v254 offset:0x3000
	ds_read_b64_tr_b16 v[244:245], v254 offset:0x3800
	s_branch .Lmla_pv_go
